# grid seam release: each XCD's last arriver adds 1 to all eight release words after its write-back; every workgroup polls its word for (generation+1)*nx - no cross-XCD ticket round trip before the rele
# speedup vs baseline: 1.0441x; 1.0072x over previous
.LBB0_88:
	v_readlane_b32 s9, v246, 5
	s_lshl_b32 s9, s9, 8
	v_readlane_b32 s10, v246, 3
	v_readlane_b32 s11, v246, 4
	s_add_u32 s10, s10, s9
	s_addc_u32 s11, s11, 0
	v_mov_b32_e32 v1, 0x1000
	v_mov_b32_e32 v3, 1
	v_sub_u32_e32 v4, 0, v2
	global_atomic_add v3, v1, v3, s[10:11] offset:1024 sc0
	v_cvt_f32_u32_e32 v1, v2
	v_rcp_iflag_f32_e32 v1, v1
	s_nop 0
	v_mul_f32_e32 v1, 0x4f7ffffe, v1
	v_cvt_u32_f32_e32 v1, v1
	v_mul_lo_u32 v4, v4, v1
	v_mul_hi_u32 v4, v1, v4
	v_add_u32_e32 v1, v1, v4
	s_waitcnt vmcnt(0)
	v_mul_hi_u32 v1, v3, v1
	v_mul_lo_u32 v4, v1, v2
	v_sub_u32_e32 v4, v3, v4
	v_add_u32_e32 v5, 1, v1
	v_cmp_ge_u32_e32 vcc, v4, v2
	v_add_u32_e32 v3, 1, v3
	s_nop 0
	v_cndmask_b32_e32 v1, v1, v5, vcc
	v_sub_u32_e32 v5, v4, v2
	v_cndmask_b32_e32 v4, v4, v5, vcc
	v_add_u32_e32 v5, 1, v1
	v_cmp_ge_u32_e32 vcc, v4, v2
	s_nop 1
	v_cndmask_b32_e32 v1, v1, v5, vcc
	v_mul_lo_u32 v4, v2, v1
	v_add_u32_e32 v2, v4, v2
	v_cmp_ne_u32_e32 vcc, v3, v2
	s_cbranch_vccnz .Lxg_nl_1
	buffer_wbl2 sc1
	buffer_inv sc1
	s_waitcnt vmcnt(0)
	v_readlane_b32 s98, v246, 3
	v_readlane_b32 s99, v246, 4
	v_mov_b32_e32 v14, 1
	v_mov_b32_e32 v6, 0x2400
	v_mov_b32_e32 v7, 0x2500
	v_mov_b32_e32 v8, 0x2600
	v_mov_b32_e32 v9, 0x2700
	v_mov_b32_e32 v10, 0x2800
	v_mov_b32_e32 v11, 0x2900
	v_mov_b32_e32 v12, 0x2a00
	v_mov_b32_e32 v13, 0x2b00
	global_atomic_add v6, v14, s[98:99]
	global_atomic_add v7, v14, s[98:99]
	global_atomic_add v8, v14, s[98:99]
	global_atomic_add v9, v14, s[98:99]
	global_atomic_add v10, v14, s[98:99]
	global_atomic_add v11, v14, s[98:99]
	global_atomic_add v12, v14, s[98:99]
	global_atomic_add v13, v14, s[98:99]
	s_mov_b64 vcc, exec
.Lxg_nl_1:
	s_and_saveexec_b64 s[12:13], vcc
	s_xor_b64 s[12:13], exec, s[12:13]
	s_cbranch_execz .LBB0_102
	s_waitcnt lgkmcnt(0)
	v_mad_u32_u24 v5, v1, v0, v0
	v_mov_b32_e32 v0, 0x2000
	global_load_dword v0, v0, s[10:11] offset:1024 sc1
	buffer_inv sc1
	s_add_u32 s18, s10, 0x2400
	s_addc_u32 s19, s11, 0
	s_waitcnt vmcnt(0)
	v_cmp_lt_u32_e32 vcc, v0, v5
	s_and_saveexec_b64 s[14:15], vcc
	s_cbranch_execz .LBB0_101
	s_add_u32 s16, s54, 0xd600200
	s_addc_u32 s17, s55, 0
	s_mov_b32 s9, 1
	s_mov_b64 s[20:21], 0
	v_mov_b32_e32 v0, 0
	s_branch .LBB0_92

.LBB0_96:
	global_load_dword v2, v0, s[18:19] sc1
	s_add_i32 s9, s9, 1
	s_mov_b64 s[28:29], -1
	s_waitcnt vmcnt(0)
	v_cmp_ge_u32_e32 vcc, v2, v5
	s_orn2_b64 s[26:27], vcc, exec
	s_branch .LBB0_91

.LBB0_150:
	v_readlane_b32 s3, v246, 5
	s_lshl_b32 s3, s3, 8
	v_readlane_b32 s8, v246, 3
	v_readlane_b32 s9, v246, 4
	s_add_u32 s8, s8, s3
	s_addc_u32 s9, s9, 0
	v_mov_b32_e32 v1, 0x1000
	v_mov_b32_e32 v3, 1
	v_sub_u32_e32 v4, 0, v2
	global_atomic_add v3, v1, v3, s[8:9] offset:1024 sc0
	v_cvt_f32_u32_e32 v1, v2
	v_rcp_iflag_f32_e32 v1, v1
	s_nop 0
	v_mul_f32_e32 v1, 0x4f7ffffe, v1
	v_cvt_u32_f32_e32 v1, v1
	v_mul_lo_u32 v4, v4, v1
	v_mul_hi_u32 v4, v1, v4
	v_add_u32_e32 v1, v1, v4
	s_waitcnt vmcnt(0)
	v_mul_hi_u32 v1, v3, v1
	v_mul_lo_u32 v4, v1, v2
	v_sub_u32_e32 v4, v3, v4
	v_add_u32_e32 v5, 1, v1
	v_cmp_ge_u32_e32 vcc, v4, v2
	v_add_u32_e32 v3, 1, v3
	s_nop 0
	v_cndmask_b32_e32 v1, v1, v5, vcc
	v_sub_u32_e32 v5, v4, v2
	v_cndmask_b32_e32 v4, v4, v5, vcc
	v_add_u32_e32 v5, 1, v1
	v_cmp_ge_u32_e32 vcc, v4, v2
	s_nop 1
	v_cndmask_b32_e32 v1, v1, v5, vcc
	v_mul_lo_u32 v4, v2, v1
	v_add_u32_e32 v2, v4, v2
	v_cmp_ne_u32_e32 vcc, v3, v2
	s_cbranch_vccnz .Lxg_nl_2
	buffer_wbl2 sc1
	buffer_inv sc1
	s_waitcnt vmcnt(0)
	v_readlane_b32 s98, v246, 3
	v_readlane_b32 s99, v246, 4
	v_mov_b32_e32 v14, 1
	v_mov_b32_e32 v6, 0x2400
	v_mov_b32_e32 v7, 0x2500
	v_mov_b32_e32 v8, 0x2600
	v_mov_b32_e32 v9, 0x2700
	v_mov_b32_e32 v10, 0x2800
	v_mov_b32_e32 v11, 0x2900
	v_mov_b32_e32 v12, 0x2a00
	v_mov_b32_e32 v13, 0x2b00
	global_atomic_add v6, v14, s[98:99]
	global_atomic_add v7, v14, s[98:99]
	global_atomic_add v8, v14, s[98:99]
	global_atomic_add v9, v14, s[98:99]
	global_atomic_add v10, v14, s[98:99]
	global_atomic_add v11, v14, s[98:99]
	global_atomic_add v12, v14, s[98:99]
	global_atomic_add v13, v14, s[98:99]
	s_mov_b64 vcc, exec
.Lxg_nl_2:
	s_and_saveexec_b64 s[10:11], vcc
	s_xor_b64 s[10:11], exec, s[10:11]
	s_cbranch_execz .LBB0_164
	s_waitcnt lgkmcnt(0)
	v_mad_u32_u24 v5, v1, v0, v0
	v_mov_b32_e32 v0, 0x2000
	global_load_dword v0, v0, s[8:9] offset:1024 sc1
	buffer_inv sc1
	s_add_u32 s16, s8, 0x2400
	s_addc_u32 s17, s9, 0
	s_waitcnt vmcnt(0)
	v_cmp_lt_u32_e32 vcc, v0, v5
	s_and_saveexec_b64 s[12:13], vcc
	s_cbranch_execz .LBB0_163
	s_add_u32 s14, s54, 0xd600200
	s_addc_u32 s15, s55, 0
	s_mov_b32 s3, 1
	s_mov_b64 s[18:19], 0
	v_mov_b32_e32 v0, 0
	s_branch .LBB0_154

.LBB0_158:
	global_load_dword v2, v0, s[16:17] sc1
	s_add_i32 s3, s3, 1
	s_mov_b64 s[26:27], -1
	s_waitcnt vmcnt(0)
	v_cmp_ge_u32_e32 vcc, v2, v5
	s_orn2_b64 s[22:23], vcc, exec
	s_branch .LBB0_153

.LBB0_223:
	v_readlane_b32 s3, v246, 5
	s_lshl_b32 s3, s3, 8
	v_readlane_b32 s6, v246, 3
	v_readlane_b32 s7, v246, 4
	s_add_u32 s6, s6, s3
	s_addc_u32 s7, s7, 0
	v_mov_b32_e32 v1, 0x1000
	v_mov_b32_e32 v3, 1
	v_sub_u32_e32 v4, 0, v2
	global_atomic_add v3, v1, v3, s[6:7] offset:1024 sc0
	v_cvt_f32_u32_e32 v1, v2
	v_rcp_iflag_f32_e32 v1, v1
	s_nop 0
	v_mul_f32_e32 v1, 0x4f7ffffe, v1
	v_cvt_u32_f32_e32 v1, v1
	v_mul_lo_u32 v4, v4, v1
	v_mul_hi_u32 v4, v1, v4
	v_add_u32_e32 v1, v1, v4
	s_waitcnt vmcnt(0)
	v_mul_hi_u32 v1, v3, v1
	v_mul_lo_u32 v4, v1, v2
	v_sub_u32_e32 v4, v3, v4
	v_add_u32_e32 v5, 1, v1
	v_cmp_ge_u32_e32 vcc, v4, v2
	v_add_u32_e32 v3, 1, v3
	s_nop 0
	v_cndmask_b32_e32 v1, v1, v5, vcc
	v_sub_u32_e32 v5, v4, v2
	v_cndmask_b32_e32 v4, v4, v5, vcc
	v_add_u32_e32 v5, 1, v1
	v_cmp_ge_u32_e32 vcc, v4, v2
	s_nop 1
	v_cndmask_b32_e32 v1, v1, v5, vcc
	v_mul_lo_u32 v4, v2, v1
	v_add_u32_e32 v2, v4, v2
	v_cmp_ne_u32_e32 vcc, v3, v2
	s_cbranch_vccnz .Lxg_nl_3
	buffer_wbl2 sc1
	buffer_inv sc1
	s_waitcnt vmcnt(0)
	v_readlane_b32 s98, v246, 3
	v_readlane_b32 s99, v246, 4
	v_mov_b32_e32 v14, 1
	v_mov_b32_e32 v6, 0x2400
	v_mov_b32_e32 v7, 0x2500
	v_mov_b32_e32 v8, 0x2600
	v_mov_b32_e32 v9, 0x2700
	v_mov_b32_e32 v10, 0x2800
	v_mov_b32_e32 v11, 0x2900
	v_mov_b32_e32 v12, 0x2a00
	v_mov_b32_e32 v13, 0x2b00
	global_atomic_add v6, v14, s[98:99]
	global_atomic_add v7, v14, s[98:99]
	global_atomic_add v8, v14, s[98:99]
	global_atomic_add v9, v14, s[98:99]
	global_atomic_add v10, v14, s[98:99]
	global_atomic_add v11, v14, s[98:99]
	global_atomic_add v12, v14, s[98:99]
	global_atomic_add v13, v14, s[98:99]
	s_mov_b64 vcc, exec
.Lxg_nl_3:
	s_and_saveexec_b64 s[8:9], vcc
	s_xor_b64 s[8:9], exec, s[8:9]
	s_cbranch_execz .LBB0_237
	s_waitcnt lgkmcnt(0)
	v_mad_u32_u24 v5, v1, v0, v0
	v_mov_b32_e32 v0, 0x2000
	global_load_dword v0, v0, s[6:7] offset:1024 sc1
	buffer_inv sc1
	s_add_u32 s14, s6, 0x2400
	s_addc_u32 s15, s7, 0
	s_waitcnt vmcnt(0)
	v_cmp_lt_u32_e32 vcc, v0, v5
	s_and_saveexec_b64 s[10:11], vcc
	s_cbranch_execz .LBB0_236
	s_add_u32 s12, s54, 0xd600200
	s_addc_u32 s13, s55, 0
	s_mov_b32 s3, 1
	s_mov_b64 s[16:17], 0
	v_mov_b32_e32 v0, 0
	s_branch .LBB0_227

.LBB0_231:
	global_load_dword v2, v0, s[14:15] sc1
	s_add_i32 s3, s3, 1
	s_mov_b64 s[22:23], -1
	s_waitcnt vmcnt(0)
	v_cmp_ge_u32_e32 vcc, v2, v5
	s_orn2_b64 s[20:21], vcc, exec
	s_branch .LBB0_226

.Lxg_nl_7:
	s_and_saveexec_b64 s[8:9], vcc
	s_xor_b64 s[8:9], exec, s[8:9]
	s_cbranch_execz .LBB0_603
	s_waitcnt lgkmcnt(0)
	v_mad_u32_u24 v5, v1, v0, v0
	v_mov_b32_e32 v0, 0x2000
	global_load_dword v0, v0, s[6:7] offset:1024 sc1
	buffer_inv sc1
	s_add_u32 s22, s6, 0x2400
	s_addc_u32 s23, s7, 0
	s_waitcnt vmcnt(0)
	v_cmp_lt_u32_e32 vcc, v0, v5
	s_and_saveexec_b64 s[10:11], vcc
	s_cbranch_execz .LBB0_602
	s_add_u32 s14, s54, 0xd600200
	s_addc_u32 s15, s55, 0
	s_mov_b32 s3, 1
	s_mov_b64 s[28:29], 0
	v_mov_b32_e32 v0, 0
	s_branch .LBB0_593

.LBB0_597:
	global_load_dword v2, v0, s[22:23] sc1
	s_add_i32 s3, s3, 1
	s_mov_b64 s[50:51], -1
	s_waitcnt vmcnt(0)
	v_cmp_ge_u32_e32 vcc, v2, v5
	s_orn2_b64 s[38:39], vcc, exec
	s_branch .LBB0_592

.Lxg_nl_8:
	s_and_saveexec_b64 s[8:9], vcc
	s_xor_b64 s[8:9], exec, s[8:9]
	s_cbranch_execz .LBB0_858
	s_waitcnt lgkmcnt(0)
	v_mad_u32_u24 v5, v1, v0, v0
	v_mov_b32_e32 v0, 0x2000
	global_load_dword v0, v0, s[6:7] offset:1024 sc1
	buffer_inv sc1
	s_add_u32 s22, s6, 0x2400
	s_addc_u32 s23, s7, 0
	s_waitcnt vmcnt(0)
	v_cmp_lt_u32_e32 vcc, v0, v5
	s_and_saveexec_b64 s[10:11], vcc
	s_cbranch_execz .LBB0_857
	s_add_u32 s20, s54, 0xd600200
	s_addc_u32 s21, s55, 0
	s_mov_b32 s3, 1
	s_mov_b64 s[60:61], 0
	v_mov_b32_e32 v0, 0
	s_branch .LBB0_848

.LBB0_852:
	global_load_dword v2, v0, s[22:23] sc1
	s_add_i32 s3, s3, 1
	s_mov_b64 s[66:67], -1
	s_waitcnt vmcnt(0)
	v_cmp_ge_u32_e32 vcc, v2, v5
	s_orn2_b64 s[64:65], vcc, exec
	s_branch .LBB0_847
